# first k-iteration of each GEMM tile peeled: first MFMA per accumulator takes C=0, no 128-register zero fill
# speedup vs baseline: 1.0298x; 1.0046x over previous
; #define PG8_STAGE(bufoff, gbase, voff) do { _Pragma("unroll") for (int _i = 0; _i < 2; ++_i) \
;         __builtin_amdgcn_global_load_lds((const unsigned*)((const char*)(gbase) + (voff)[_i]), (LAS unsigned*)(lds + (bufoff) + ldsw + _i * 8192), 16, 0, 0); } while (0)
; #define PG8_WAIT_V(n) asm volatile("s_waitcnt vmcnt(" #n ")" ::: "memory")
; #define PG8_BAR __builtin_amdgcn_s_barrier()
; #define PG8_RECFG() int phx = ph; int lx = l; unsigned char* wsx = ws; unsigned char* wgx = wg; asm volatile("" : "+s"(phx), "+s"(lx), "+s"(wsx), "+s"(wgx)); const Cfg gx = gemm_cfg(phx, wsx, wgx, lx); \
;         const size_t tstepA = (size_t)BM * gx.lda * 2, tstepB = (size_t)BM * gx.ldb * 2
; DI void gemm_phase(LAS unsigned char* lds, int ph, unsigned char* ws, unsigned char* wg, int l, const float* pscale, int G, int cidx, int nx) {
;     ...
;     f32x4 acc[2][2][4][2];
; #pragma unroll
;     for (int a = 0; a < 2; ++a)
; #pragma unroll
;         for (int b = 0; b < 2; ++b)
; #pragma unroll
;             for (int m = 0; m < 4; ++m)
; #pragma unroll
;                 for (int n = 0; n < 2; ++n) acc[a][b][m][n] = (f32x4){0.f, 0.f, 0.f, 0.f};
;     bf16x8 At[4][2], B0[2][2], B1[2][2];
;     const char* cA; const char* cB; { PG8_RECFG(); cA = PG8_ABASE(cur); cB = PG8_BBASE(cur); }
;     PG8_STAGE(PG8_SB(0, 0), cB, voffB); PG8_STAGE(PG8_SB(0, 1), cB + hstepB, voffB); PG8_STAGE(PG8_SA(0, 0), cA, voffA); PG8_STAGE(PG8_SA(0, 1), cA + hstepA, voffA);
;     if (wr == 1) PG8_BAR;
;     PG8_WAIT_V(2); PG8_BAR;
;     PG8_STAGE(PG8_SB(1, 0), cB + kstep, voffB); PG8_STAGE(PG8_SA(1, 0), cA + kstep, voffA); PG8_STAGE(PG8_SB(1, 1), cB + hstepB + kstep, voffB);
;     PG8_WAIT_V(6); PG8_BAR;
;     for (;;) {
;         const bool has_next = S.next(ui + 1, nxt);
;         const char* nA = cA; const char* nB = cB; if (has_next) { PG8_RECFG(); nA = PG8_ABASE(nxt); nB = PG8_BBASE(nxt); }
;         for (int t = 0; t < nt; t += 2) {
.LBB0_499:
	s_lshl_b32 s0, s17, 8
	s_or_b32 s66, s0, s97
	s_lshl_b32 s69, s18, 8
	v_or_b32_e32 v140, s66, v172
	s_waitcnt vmcnt(0)
	s_add_i32 s69, s69, s92
	v_ashrrev_i32_e32 v141, 31, v140
	s_mov_b32 s38, 0
	s_branch .Lpeel_501

; #define PG8_STAGE(bufoff, gbase, voff) do { _Pragma("unroll") for (int _i = 0; _i < 2; ++_i) \
;         __builtin_amdgcn_global_load_lds((const unsigned*)((const char*)(gbase) + (voff)[_i]), (LAS unsigned*)(lds + (bufoff) + ldsw + _i * 8192), 16, 0, 0); } while (0)
; #define PG8_LDA(dst, b, h) do { _Pragma("unroll") for (int m = 0; m < 4; ++m) _Pragma("unroll") for (int k = 0; k < 2; ++k) dst[m][k] = *(const LAS bf16x8*)(lds + PG8_SA(b, h) + aoff + m * 2048 + k * 1024); } while (0)
; #define PG8_LDB(dst, b, h) do { _Pragma("unroll") for (int n = 0; n < 2; ++n) _Pragma("unroll") for (int k = 0; k < 2; ++k) dst[n][k] = *(const LAS bf16x8*)(lds + PG8_SB(b, h) + boff + n * 2048 + k * 1024); } while (0)
; #define PG8_MMA(ai, bj, At, Bt) do { __builtin_amdgcn_s_setprio(1); _Pragma("unroll") for (int m = 0; m < 4; ++m) _Pragma("unroll") for (int n = 0; n < 2; ++n) _Pragma("unroll") for (int k = 0; k < 2; ++k) \
;         acc[ai][bj][m][n] = __builtin_amdgcn_mfma_f32_16x16x32_bf16(Bt[n][k], At[m][k], acc[ai][bj][m][n], 0, 0, 0); __builtin_amdgcn_s_setprio(0); } while (0)
; #define PG8_WAIT_V(n) asm volatile("s_waitcnt vmcnt(" #n ")" ::: "memory")
; #define PG8_WAIT_L(n) asm volatile("s_waitcnt lgkmcnt(" #n ")" ::: "memory")
; #define PG8_BAR __builtin_amdgcn_s_barrier()
; #define PG8_SCHED __builtin_amdgcn_sched_barrier(0)
; DI void gemm_phase(LAS unsigned char* lds, int ph, unsigned char* ws, unsigned char* wg, int l, const float* pscale, int G, int cidx, int nx) {
;     ...
;             if (zAb != 0 && t != 0 && (t & ntzm) == 0) { unsigned char* wsx = ws; asm volatile("" : "+s"(wsx)); int frx = fr; asm volatile("" : "+v"(frx)); merge_carry(acc, wsx, cur, (t >> lz) - 1, wr, wc, frx, fq); }
;             PG8_LDB(B0, 0, 0); PG8_LDB(B1, 0, 1); PG8_SCHED; PG8_LDA(At, 0, 0); PG8_STAGE(PG8_SA(1, 1), a1 + hstepA, voffA);
;             PG8_WAIT_V(8); PG8_WAIT_L(0); PG8_BAR; PG8_MMA(0, 0, At, B0); PG8_MMA(0, 1, At, B1); PG8_BAR; PG8_SCHED;
;             PG8_LDA(At, 0, 1); PG8_STAGE(PG8_SB(0, 0), b2, voffB); PG8_STAGE(PG8_SB(0, 1), b2 + hstepB, voffB); PG8_STAGE(PG8_SA(0, 0), a2, voffA);
;             PG8_WAIT_V(8); PG8_WAIT_L(0); PG8_BAR; PG8_MMA(1, 0, At, B0); PG8_MMA(1, 1, At, B1); PG8_BAR; PG8_SCHED;
.Lpeel_505:
	s_cmp_lg_u32 s38, 0
	s_cselect_b64 s[18:19], -1, 0
	s_and_b64 s[18:19], s[50:51], s[18:19]
	s_and_b32 s12, s38, s83
	s_cmp_eq_u32 s12, 0
	s_cselect_b64 s[20:21], -1, 0
	s_and_b64 s[18:19], s[18:19], s[20:21]
	s_andn2_b64 vcc, exec, s[18:19]
	s_branch .Lpeel_500
.Lpeel_500:
	s_add_i32 s12, s38, 1
	s_lshr_b32 s18, s12, s76
	s_mul_i32 s19, s53, s18
	s_mul_hi_u32 s20, s52, s18
	s_add_i32 s20, s20, s19
	s_mul_i32 s18, s52, s18
	s_add_u32 s18, s42, s18
	s_addc_u32 s19, s43, s20
	s_and_b32 s12, s12, s83
	s_lshl_b32 s12, s12, 7
	s_add_u32 s12, s18, s12
	s_addc_u32 s19, s19, 0
	v_add_u32_e32 v80, s91, v173
	s_add_i32 s20, 0, 0x14000
	ds_read_b128 v[132:135], v80
	ds_read_b128 v[136:139], v80 offset:1024
	ds_read_b128 v[142:145], v80 offset:2048
	ds_read_b128 v[158:161], v80 offset:3072
	v_add_u32_e32 v80, s20, v173
	ds_read_b128 v[176:179], v80
	ds_read_b128 v[180:183], v80 offset:1024
	ds_read_b128 v[184:187], v80 offset:2048
	ds_read_b128 v[188:191], v80 offset:3072
	s_add_u32 s18, s12, s7
	s_addc_u32 s19, s19, 0
	s_add_i32 m0, s79, 0xc000
	ds_read_b128 v[192:195], v174
	ds_read_b128 v[196:199], v174 offset:1024
	ds_read_b128 v[200:203], v174 offset:2048
	ds_read_b128 v[204:207], v174 offset:3072
	ds_read_b128 v[208:211], v174 offset:4096
	ds_read_b128 v[212:215], v174 offset:5120
	ds_read_b128 v[216:219], v174 offset:6144
	ds_read_b128 v[220:223], v174 offset:7168
	global_load_lds_dwordx4 v150, s[18:19]
	s_add_i32 m0, s79, 0xe000
	s_nop 0
	global_load_lds_dwordx4 v154, s[18:19]
	s_waitcnt vmcnt(8)
	s_waitcnt lgkmcnt(0)
	s_barrier
	s_setprio 1
	s_waitcnt lgkmcnt(0)
	v_mfma_f32_16x16x32_bf16 v[128:131], v[132:135], v[192:195], 0
	v_mfma_f32_16x16x32_bf16 v[124:127], v[142:145], v[192:195], 0
	v_mfma_f32_16x16x32_bf16 v[112:115], v[132:135], v[200:203], 0
	v_mfma_f32_16x16x32_bf16 v[108:111], v[142:145], v[200:203], 0
	v_mfma_f32_16x16x32_bf16 v[96:99], v[132:135], v[208:211], 0
	v_mfma_f32_16x16x32_bf16 v[92:95], v[142:145], v[208:211], 0
	v_mfma_f32_16x16x32_bf16 v[76:79], v[132:135], v[216:219], 0
	v_mfma_f32_16x16x32_bf16 v[72:75], v[142:145], v[216:219], 0
	v_mfma_f32_16x16x32_bf16 v[128:131], v[136:139], v[196:199], v[128:131]
	v_mfma_f32_16x16x32_bf16 v[124:127], v[158:161], v[196:199], v[124:127]
	v_mfma_f32_16x16x32_bf16 v[112:115], v[136:139], v[204:207], v[112:115]
	v_mfma_f32_16x16x32_bf16 v[108:111], v[158:161], v[204:207], v[108:111]
	v_mfma_f32_16x16x32_bf16 v[96:99], v[136:139], v[212:215], v[96:99]
	v_mfma_f32_16x16x32_bf16 v[92:95], v[158:161], v[212:215], v[92:95]
	v_mfma_f32_16x16x32_bf16 v[76:79], v[136:139], v[220:223], v[76:79]
	v_mfma_f32_16x16x32_bf16 v[72:75], v[158:161], v[220:223], v[72:75]
	v_mfma_f32_16x16x32_bf16 v[120:123], v[176:179], v[192:195], 0
	v_mfma_f32_16x16x32_bf16 v[116:119], v[184:187], v[192:195], 0
	v_mfma_f32_16x16x32_bf16 v[104:107], v[176:179], v[200:203], 0
	v_mfma_f32_16x16x32_bf16 v[100:103], v[184:187], v[200:203], 0
	v_mfma_f32_16x16x32_bf16 v[88:91], v[176:179], v[208:211], 0
	v_mfma_f32_16x16x32_bf16 v[82:85], v[184:187], v[208:211], 0
	v_mfma_f32_16x16x32_bf16 v[68:71], v[176:179], v[216:219], 0
	v_mfma_f32_16x16x32_bf16 v[64:67], v[184:187], v[216:219], 0
	v_mfma_f32_16x16x32_bf16 v[120:123], v[180:183], v[196:199], v[120:123]
	v_mfma_f32_16x16x32_bf16 v[116:119], v[188:191], v[196:199], v[116:119]
	v_mfma_f32_16x16x32_bf16 v[104:107], v[180:183], v[204:207], v[104:107]
	v_mfma_f32_16x16x32_bf16 v[100:103], v[188:191], v[204:207], v[100:103]
	v_mfma_f32_16x16x32_bf16 v[88:91], v[180:183], v[212:215], v[88:91]
	v_mfma_f32_16x16x32_bf16 v[82:85], v[188:191], v[212:215], v[82:85]
	v_mfma_f32_16x16x32_bf16 v[68:71], v[180:183], v[220:223], v[68:71]
	v_mfma_f32_16x16x32_bf16 v[64:67], v[188:191], v[220:223], v[64:67]
	s_setprio 0
	s_barrier
	s_add_i32 s12, s91, s78
	s_mov_b32 m0, s12
	ds_read_b128 v[192:195], v174 offset:16384
	ds_read_b128 v[196:199], v174 offset:17408
	ds_read_b128 v[200:203], v174 offset:18432
	ds_read_b128 v[204:207], v174 offset:19456
	ds_read_b128 v[208:211], v174 offset:20480
	ds_read_b128 v[212:215], v174 offset:21504
	ds_read_b128 v[216:219], v174 offset:22528
	ds_read_b128 v[220:223], v174 offset:23552
	global_load_lds_dwordx4 v152, s[64:65]
	s_add_i32 m0, s12, 0x2000
	s_add_u32 s18, s64, s77
	s_addc_u32 s19, s65, 0
	s_add_i32 s12, s20, s78
	global_load_lds_dwordx4 v156, s[64:65]
	s_mov_b32 m0, s12
	s_nop 0
	global_load_lds_dwordx4 v152, s[18:19]
	s_add_i32 m0, s12, 0x2000
	s_nop 0
	global_load_lds_dwordx4 v156, s[18:19]
	s_mov_b32 m0, s79
	s_nop 0
	global_load_lds_dwordx4 v150, s[0:1]
	s_mov_b32 m0, s80
	s_nop 0
	global_load_lds_dwordx4 v154, s[0:1]
	s_waitcnt vmcnt(8)
	s_waitcnt lgkmcnt(0)
	s_barrier
; #define PG8_STAGE(bufoff, gbase, voff) do { _Pragma("unroll") for (int _i = 0; _i < 2; ++_i) \
;         __builtin_amdgcn_global_load_lds((const unsigned*)((const char*)(gbase) + (voff)[_i]), (LAS unsigned*)(lds + (bufoff) + ldsw + _i * 8192), 16, 0, 0); } while (0)
; #define PG8_LDA(dst, b, h) do { _Pragma("unroll") for (int m = 0; m < 4; ++m) _Pragma("unroll") for (int k = 0; k < 2; ++k) dst[m][k] = *(const LAS bf16x8*)(lds + PG8_SA(b, h) + aoff + m * 2048 + k * 1024); } while (0)
; #define PG8_LDB(dst, b, h) do { _Pragma("unroll") for (int n = 0; n < 2; ++n) _Pragma("unroll") for (int k = 0; k < 2; ++k) dst[n][k] = *(const LAS bf16x8*)(lds + PG8_SB(b, h) + boff + n * 2048 + k * 1024); } while (0)
; #define PG8_MMA(ai, bj, At, Bt) do { __builtin_amdgcn_s_setprio(1); _Pragma("unroll") for (int m = 0; m < 4; ++m) _Pragma("unroll") for (int n = 0; n < 2; ++n) _Pragma("unroll") for (int k = 0; k < 2; ++k) \
;         acc[ai][bj][m][n] = __builtin_amdgcn_mfma_f32_16x16x32_bf16(Bt[n][k], At[m][k], acc[ai][bj][m][n], 0, 0, 0); __builtin_amdgcn_s_setprio(0); } while (0)
; #define PG8_WAIT_V(n) asm volatile("s_waitcnt vmcnt(" #n ")" ::: "memory")
; #define PG8_WAIT_L(n) asm volatile("s_waitcnt lgkmcnt(" #n ")" ::: "memory")
; #define PG8_BAR __builtin_amdgcn_s_barrier()
; #define PG8_SCHED __builtin_amdgcn_sched_barrier(0)
; DI void gemm_phase(LAS unsigned char* lds, int ph, unsigned char* ws, unsigned char* wg, int l, const float* pscale, int G, int cidx, int nx) {
;     ...
;             PG8_WAIT_V(8); PG8_WAIT_L(0); PG8_BAR; PG8_MMA(1, 0, At, B0); PG8_MMA(1, 1, At, B1); PG8_BAR; PG8_SCHED;
;             PG8_LDB(B0, 1, 0); PG8_LDB(B1, 1, 1); PG8_SCHED; PG8_LDA(At, 1, 0); PG8_STAGE(PG8_SA(0, 1), a2 + hstepA, voffA);
;             PG8_WAIT_V(8); PG8_WAIT_L(0); PG8_BAR; PG8_MMA(0, 0, At, B0); PG8_MMA(0, 1, At, B1); PG8_BAR; PG8_SCHED;
	s_setprio 1
	s_waitcnt lgkmcnt(0)
	v_mfma_f32_16x16x32_bf16 v[60:63], v[132:135], v[192:195], 0
	v_mfma_f32_16x16x32_bf16 v[56:59], v[142:145], v[192:195], 0
	v_mfma_f32_16x16x32_bf16 v[44:47], v[132:135], v[200:203], 0
	v_mfma_f32_16x16x32_bf16 v[40:43], v[142:145], v[200:203], 0
	v_mfma_f32_16x16x32_bf16 v[28:31], v[132:135], v[208:211], 0
	v_mfma_f32_16x16x32_bf16 v[24:27], v[142:145], v[208:211], 0
	v_mfma_f32_16x16x32_bf16 v[12:15], v[132:135], v[216:219], 0
	v_mfma_f32_16x16x32_bf16 v[8:11], v[142:145], v[216:219], 0
	v_mfma_f32_16x16x32_bf16 v[60:63], v[136:139], v[196:199], v[60:63]
	v_mfma_f32_16x16x32_bf16 v[56:59], v[158:161], v[196:199], v[56:59]
	v_mfma_f32_16x16x32_bf16 v[44:47], v[136:139], v[204:207], v[44:47]
	v_mfma_f32_16x16x32_bf16 v[40:43], v[158:161], v[204:207], v[40:43]
	v_mfma_f32_16x16x32_bf16 v[28:31], v[136:139], v[212:215], v[28:31]
	v_mfma_f32_16x16x32_bf16 v[24:27], v[158:161], v[212:215], v[24:27]
	v_mfma_f32_16x16x32_bf16 v[12:15], v[136:139], v[220:223], v[12:15]
	v_mfma_f32_16x16x32_bf16 v[8:11], v[158:161], v[220:223], v[8:11]
	v_mfma_f32_16x16x32_bf16 v[52:55], v[176:179], v[192:195], 0
	v_mfma_f32_16x16x32_bf16 v[48:51], v[184:187], v[192:195], 0
	v_mfma_f32_16x16x32_bf16 v[36:39], v[176:179], v[200:203], 0
	v_mfma_f32_16x16x32_bf16 v[32:35], v[184:187], v[200:203], 0
	v_mfma_f32_16x16x32_bf16 v[20:23], v[176:179], v[208:211], 0
	v_mfma_f32_16x16x32_bf16 v[16:19], v[184:187], v[208:211], 0
	v_mfma_f32_16x16x32_bf16 v[4:7], v[176:179], v[216:219], 0
	v_mfma_f32_16x16x32_bf16 v[0:3], v[184:187], v[216:219], 0
	v_mfma_f32_16x16x32_bf16 v[52:55], v[180:183], v[196:199], v[52:55]
	v_mfma_f32_16x16x32_bf16 v[48:51], v[188:191], v[196:199], v[48:51]
	v_mfma_f32_16x16x32_bf16 v[36:39], v[180:183], v[204:207], v[36:39]
	v_mfma_f32_16x16x32_bf16 v[32:35], v[188:191], v[204:207], v[32:35]
	v_mfma_f32_16x16x32_bf16 v[20:23], v[180:183], v[212:215], v[20:23]
	v_mfma_f32_16x16x32_bf16 v[16:19], v[188:191], v[212:215], v[16:19]
	v_mfma_f32_16x16x32_bf16 v[4:7], v[180:183], v[220:223], v[4:7]
	v_mfma_f32_16x16x32_bf16 v[0:3], v[188:191], v[220:223], v[0:3]
	s_setprio 0
	s_barrier
	s_add_i32 s12, 0, 0x18000
	v_add_u32_e32 v80, s12, v173
	s_add_i32 s18, 0, 0x1c000
	ds_read_b128 v[132:135], v80
	ds_read_b128 v[136:139], v80 offset:1024
	ds_read_b128 v[142:145], v80 offset:2048
	ds_read_b128 v[158:161], v80 offset:3072
	v_add_u32_e32 v80, s18, v173
	ds_read_b128 v[176:179], v80
	ds_read_b128 v[180:183], v80 offset:1024
	ds_read_b128 v[184:187], v80 offset:2048
	ds_read_b128 v[188:191], v80 offset:3072
	s_add_u32 s0, s0, s7
	s_addc_u32 s1, s1, 0
	s_mov_b32 m0, s81
	ds_read_b128 v[192:195], v174 offset:32768
	ds_read_b128 v[196:199], v174 offset:33792
	ds_read_b128 v[200:203], v174 offset:34816
	ds_read_b128 v[204:207], v174 offset:35840
	ds_read_b128 v[208:211], v174 offset:36864
	ds_read_b128 v[212:215], v174 offset:37888
	ds_read_b128 v[216:219], v174 offset:38912
	ds_read_b128 v[220:223], v174 offset:39936
	global_load_lds_dwordx4 v150, s[0:1]
	s_mov_b32 m0, s82
	s_nop 0
	global_load_lds_dwordx4 v154, s[0:1]
	s_waitcnt vmcnt(8)
	s_waitcnt lgkmcnt(0)
	s_barrier
	s_setprio 1
	s_waitcnt lgkmcnt(0)
	v_mfma_f32_16x16x32_bf16 v[128:131], v[132:135], v[192:195], v[128:131]
	v_mfma_f32_16x16x32_bf16 v[124:127], v[142:145], v[192:195], v[124:127]
	v_mfma_f32_16x16x32_bf16 v[112:115], v[132:135], v[200:203], v[112:115]
	v_mfma_f32_16x16x32_bf16 v[108:111], v[142:145], v[200:203], v[108:111]
	v_mfma_f32_16x16x32_bf16 v[96:99], v[132:135], v[208:211], v[96:99]
	v_mfma_f32_16x16x32_bf16 v[92:95], v[142:145], v[208:211], v[92:95]
	v_mfma_f32_16x16x32_bf16 v[76:79], v[132:135], v[216:219], v[76:79]
	v_mfma_f32_16x16x32_bf16 v[72:75], v[142:145], v[216:219], v[72:75]
	v_mfma_f32_16x16x32_bf16 v[128:131], v[136:139], v[196:199], v[128:131]
	v_mfma_f32_16x16x32_bf16 v[124:127], v[158:161], v[196:199], v[124:127]
	v_mfma_f32_16x16x32_bf16 v[112:115], v[136:139], v[204:207], v[112:115]
	v_mfma_f32_16x16x32_bf16 v[108:111], v[158:161], v[204:207], v[108:111]
	v_mfma_f32_16x16x32_bf16 v[96:99], v[136:139], v[212:215], v[96:99]
	v_mfma_f32_16x16x32_bf16 v[92:95], v[158:161], v[212:215], v[92:95]
	v_mfma_f32_16x16x32_bf16 v[76:79], v[136:139], v[220:223], v[76:79]
	v_mfma_f32_16x16x32_bf16 v[72:75], v[158:161], v[220:223], v[72:75]
	v_mfma_f32_16x16x32_bf16 v[120:123], v[176:179], v[192:195], v[120:123]
	v_mfma_f32_16x16x32_bf16 v[116:119], v[184:187], v[192:195], v[116:119]
	v_mfma_f32_16x16x32_bf16 v[104:107], v[176:179], v[200:203], v[104:107]
	v_mfma_f32_16x16x32_bf16 v[100:103], v[184:187], v[200:203], v[100:103]
	v_mfma_f32_16x16x32_bf16 v[86:89], v[176:179], v[208:211], v[88:91]
	v_mfma_f32_16x16x32_bf16 v[82:85], v[184:187], v[208:211], v[82:85]
	v_mfma_f32_16x16x32_bf16 v[68:71], v[176:179], v[216:219], v[68:71]
	v_mfma_f32_16x16x32_bf16 v[64:67], v[184:187], v[216:219], v[64:67]
	v_mfma_f32_16x16x32_bf16 v[120:123], v[180:183], v[196:199], v[120:123]
	v_mfma_f32_16x16x32_bf16 v[116:119], v[188:191], v[196:199], v[116:119]
	v_mfma_f32_16x16x32_bf16 v[104:107], v[180:183], v[204:207], v[104:107]
	v_mfma_f32_16x16x32_bf16 v[100:103], v[188:191], v[204:207], v[100:103]
	v_mfma_f32_16x16x32_bf16 v[88:91], v[180:183], v[212:215], v[86:89]
	v_mfma_f32_16x16x32_bf16 v[84:87], v[188:191], v[212:215], v[82:85]
	v_mfma_f32_16x16x32_bf16 v[68:71], v[180:183], v[220:223], v[68:71]
	v_mfma_f32_16x16x32_bf16 v[64:67], v[188:191], v[220:223], v[64:67]
	s_setprio 0
	s_barrier
; #define PG8_STAGE(bufoff, gbase, voff) do { _Pragma("unroll") for (int _i = 0; _i < 2; ++_i) \
;         __builtin_amdgcn_global_load_lds((const unsigned*)((const char*)(gbase) + (voff)[_i]), (LAS unsigned*)(lds + (bufoff) + ldsw + _i * 8192), 16, 0, 0); } while (0)
; #define PG8_LDA(dst, b, h) do { _Pragma("unroll") for (int m = 0; m < 4; ++m) _Pragma("unroll") for (int k = 0; k < 2; ++k) dst[m][k] = *(const LAS bf16x8*)(lds + PG8_SA(b, h) + aoff + m * 2048 + k * 1024); } while (0)
; #define PG8_MMA(ai, bj, At, Bt) do { __builtin_amdgcn_s_setprio(1); _Pragma("unroll") for (int m = 0; m < 4; ++m) _Pragma("unroll") for (int n = 0; n < 2; ++n) _Pragma("unroll") for (int k = 0; k < 2; ++k) \
;         acc[ai][bj][m][n] = __builtin_amdgcn_mfma_f32_16x16x32_bf16(Bt[n][k], At[m][k], acc[ai][bj][m][n], 0, 0, 0); __builtin_amdgcn_s_setprio(0); } while (0)
; #define PG8_WAIT_V(n) asm volatile("s_waitcnt vmcnt(" #n ")" ::: "memory")
; #define PG8_WAIT_L(n) asm volatile("s_waitcnt lgkmcnt(" #n ")" ::: "memory")
; #define PG8_BAR __builtin_amdgcn_s_barrier()
; #define PG8_SCHED __builtin_amdgcn_sched_barrier(0)
; DI void gemm_phase(LAS unsigned char* lds, int ph, unsigned char* ws, unsigned char* wg, int l, const float* pscale, int G, int cidx, int nx) {
;     ...
;             PG8_LDA(At, 1, 1); PG8_STAGE(PG8_SB(1, 0), b3, voffB); PG8_STAGE(PG8_SB(1, 1), b3 + hstepB, voffB); PG8_STAGE(PG8_SA(1, 0), a3, voffA);
;             PG8_WAIT_V(8); PG8_WAIT_L(0); PG8_BAR; PG8_MMA(1, 0, At, B0); PG8_MMA(1, 1, At, B1); PG8_BAR; PG8_SCHED;
;         }
	s_sub_u32 s20, s0, s7
	s_subb_u32 s21, s1, 0
	s_add_u32 s20, s20, s4
	s_addc_u32 s21, s21, s5
	s_add_u32 s0, s64, s4
	s_addc_u32 s1, s65, s5
	s_add_i32 s19, s12, s78
	s_mov_b32 m0, s19
	ds_read_b128 v[192:195], v174 offset:49152
	ds_read_b128 v[196:199], v174 offset:50176
	ds_read_b128 v[200:203], v174 offset:51200
	ds_read_b128 v[204:207], v174 offset:52224
	ds_read_b128 v[208:211], v174 offset:53248
	ds_read_b128 v[212:215], v174 offset:54272
	ds_read_b128 v[216:219], v174 offset:55296
	ds_read_b128 v[220:223], v174 offset:56320
	global_load_lds_dwordx4 v152, s[0:1]
	s_add_i32 m0, s19, 0x2000
	s_add_i32 s19, s18, s78
	global_load_lds_dwordx4 v156, s[0:1]
	s_add_u32 s0, s0, s77
	s_addc_u32 s1, s1, 0
	s_mov_b32 m0, s19
	s_nop 0
	global_load_lds_dwordx4 v152, s[0:1]
	s_add_i32 m0, s19, 0x2000
	s_nop 0
	global_load_lds_dwordx4 v156, s[0:1]
	s_mov_b32 m0, s93
	s_nop 0
	global_load_lds_dwordx4 v150, s[20:21]
	s_mov_b32 m0, s94
	s_nop 0
	global_load_lds_dwordx4 v154, s[20:21]
	s_waitcnt vmcnt(8)
	s_waitcnt lgkmcnt(0)
	s_barrier
	s_setprio 1
	s_waitcnt lgkmcnt(0)
	v_mfma_f32_16x16x32_bf16 v[60:63], v[132:135], v[192:195], v[60:63]
	v_mfma_f32_16x16x32_bf16 v[56:59], v[142:145], v[192:195], v[56:59]
	v_mfma_f32_16x16x32_bf16 v[44:47], v[132:135], v[200:203], v[44:47]
	v_mfma_f32_16x16x32_bf16 v[40:43], v[142:145], v[200:203], v[40:43]
	v_mfma_f32_16x16x32_bf16 v[28:31], v[132:135], v[208:211], v[28:31]
	v_mfma_f32_16x16x32_bf16 v[24:27], v[142:145], v[208:211], v[24:27]
	v_mfma_f32_16x16x32_bf16 v[12:15], v[132:135], v[216:219], v[12:15]
	v_mfma_f32_16x16x32_bf16 v[8:11], v[142:145], v[216:219], v[8:11]
	v_mfma_f32_16x16x32_bf16 v[60:63], v[136:139], v[196:199], v[60:63]
	v_mfma_f32_16x16x32_bf16 v[56:59], v[158:161], v[196:199], v[56:59]
	v_mfma_f32_16x16x32_bf16 v[44:47], v[136:139], v[204:207], v[44:47]
	v_mfma_f32_16x16x32_bf16 v[40:43], v[158:161], v[204:207], v[40:43]
	v_mfma_f32_16x16x32_bf16 v[28:31], v[136:139], v[212:215], v[28:31]
	v_mfma_f32_16x16x32_bf16 v[24:27], v[158:161], v[212:215], v[24:27]
	v_mfma_f32_16x16x32_bf16 v[12:15], v[136:139], v[220:223], v[12:15]
	v_mfma_f32_16x16x32_bf16 v[8:11], v[158:161], v[220:223], v[8:11]
	v_mfma_f32_16x16x32_bf16 v[52:55], v[176:179], v[192:195], v[52:55]
	v_mfma_f32_16x16x32_bf16 v[48:51], v[184:187], v[192:195], v[48:51]
	v_mfma_f32_16x16x32_bf16 v[36:39], v[176:179], v[200:203], v[36:39]
	v_mfma_f32_16x16x32_bf16 v[32:35], v[184:187], v[200:203], v[32:35]
	v_mfma_f32_16x16x32_bf16 v[20:23], v[176:179], v[208:211], v[20:23]
	v_mfma_f32_16x16x32_bf16 v[16:19], v[184:187], v[208:211], v[16:19]
	v_mfma_f32_16x16x32_bf16 v[4:7], v[176:179], v[216:219], v[4:7]
	v_mfma_f32_16x16x32_bf16 v[0:3], v[184:187], v[216:219], v[0:3]
	v_mfma_f32_16x16x32_bf16 v[52:55], v[180:183], v[196:199], v[52:55]
	v_mfma_f32_16x16x32_bf16 v[48:51], v[188:191], v[196:199], v[48:51]
	v_mfma_f32_16x16x32_bf16 v[36:39], v[180:183], v[204:207], v[36:39]
	v_mfma_f32_16x16x32_bf16 v[32:35], v[188:191], v[204:207], v[32:35]
	v_mfma_f32_16x16x32_bf16 v[20:23], v[180:183], v[212:215], v[20:23]
	v_mfma_f32_16x16x32_bf16 v[16:19], v[188:191], v[212:215], v[16:19]
	v_mfma_f32_16x16x32_bf16 v[4:7], v[180:183], v[220:223], v[4:7]
	v_mfma_f32_16x16x32_bf16 v[0:3], v[188:191], v[220:223], v[0:3]
	s_setprio 0
	s_barrier
	s_add_i32 s38, s38, 2
	s_cmp_ge_u32 s38, s75
	s_cbranch_scc1 .LBB0_507
	s_branch .LBB0_501
